# norm1/norm2 phases: serialized per-chunk gamma/scale/shift loads and the K-half partial fold loads hoisted and batched (renamed to free VGPRs, vmcnt recounted)
# speedup vs baseline: 1.0118x; 1.0118x over previous
.LBB0_136:
	s_lshl_b64 s[0:1], s[20:21], 2
	s_add_u32 s8, s4, s0
	s_addc_u32 s9, s5, s1
	s_add_u32 s20, s8, 0x2000
	global_load_dwordx4 v[78:81], v[40:41], off
	s_addc_u32 s21, s9, 0
	global_load_dwordx4 v[82:85], v144, s[20:21]
	global_load_dwordx4 v[92:95], v144, s[8:9]
	global_load_dwordx4 v[100:103], v[40:41], off offset:1024
	global_load_dwordx4 v[104:107], v59, s[20:21]
	global_load_dwordx4 v[108:111], v144, s[8:9] offset:1024
	global_load_dwordx4 v[112:115], v[40:41], off offset:2048
	global_load_dwordx4 v[116:119], v63, s[20:21]
	global_load_dwordx4 v[120:123], v144, s[8:9] offset:2048
	global_load_dwordx4 v[124:127], v[40:41], off offset:3072
	global_load_dwordx4 v[128:131], v86, s[20:21]
	global_load_dwordx4 v[132:135], v144, s[8:9] offset:3072
	global_load_dwordx4 v[136:139], v[66:67], off
	global_load_dwordx4 v[140:143], v87, s[20:21]
	global_load_dwordx4 v[188:191], v87, s[8:9]
	global_load_dwordx4 v[192:195], v[68:69], off
	global_load_dwordx4 v[196:199], v88, s[20:21]
	global_load_dwordx4 v[200:203], v88, s[8:9]
	global_load_dwordx4 v[204:207], v[70:71], off
	global_load_dwordx4 v[208:211], v89, s[20:21]
	global_load_dwordx4 v[212:215], v89, s[8:9]
	global_load_dwordx4 v[216:219], v[72:73], off
	global_load_dwordx4 v[220:223], v90, s[20:21]
	global_load_dwordx4 v[224:227], v90, s[8:9]
	ds_bpermute_b32 v33, v37, v32
	s_ashr_i32 s19, s18, 31
	s_lshl_b64 s[0:1], s[18:19], 12
	v_lshl_add_u64 v[96:97], v[74:75], 0, s[0:1]
	s_add_i32 s12, s12, s34
	s_waitcnt lgkmcnt(0)
	v_add_f32_e32 v32, v32, v33
	ds_bpermute_b32 v33, v45, v32
	s_add_i32 s28, s28, s3
	s_add_u32 s16, s16, s40
	s_addc_u32 s17, s17, s41
	s_cmpk_lt_i32 s12, 0x3000
	s_waitcnt lgkmcnt(0)
	v_add_f32_e32 v32, v32, v33
	ds_bpermute_b32 v33, v47, v32
	v_lshl_add_u64 v[76:77], v[76:77], 0, s[42:43]
	s_waitcnt lgkmcnt(0)
	v_add_f32_e32 v32, v32, v33
	ds_bpermute_b32 v33, v49, v32
	s_waitcnt lgkmcnt(0)
	v_add_f32_e32 v32, v32, v33
	ds_bpermute_b32 v33, v51, v32
	s_waitcnt lgkmcnt(0)
	v_add_f32_e32 v32, v32, v33
	ds_bpermute_b32 v33, v55, v32
	s_waitcnt lgkmcnt(0)
	v_add_f32_e32 v32, v32, v33
	v_fmamk_f32 v32, v32, 0x3a000000, v181
	v_mul_f32_e32 v33, 0x4b800000, v32
	v_cmp_gt_f32_e32 vcc, s72, v32
	s_waitcnt vmcnt(22)
	v_pk_add_f32 v[34:35], v[82:83], 1.0 op_sel_hi:[1,0]
	v_cndmask_b32_e32 v32, v32, v33, vcc
	v_rsq_f32_e32 v32, v32
	s_nop 0
	v_mul_f32_e32 v33, 0x45800000, v32
	v_cndmask_b32_e32 v98, v32, v33, vcc
	v_pk_mul_f32 v[30:31], v[30:31], v[98:99] op_sel_hi:[1,0]
	v_pk_mul_f32 v[28:29], v[28:29], v[98:99] op_sel_hi:[1,0]
	v_pk_mul_f32 v[30:31], v[80:81], v[30:31]
	v_pk_mul_f32 v[28:29], v[78:79], v[28:29]
	v_pk_add_f32 v[32:33], v[84:85], 1.0 op_sel_hi:[1,0]
	s_waitcnt vmcnt(21)
	v_pk_fma_f32 v[28:29], v[34:35], v[28:29], v[92:93]
	v_pk_fma_f32 v[30:31], v[32:33], v[30:31], v[94:95]
	v_cvt_pk_bf16_f32 v28, v28, v29
	v_cvt_pk_bf16_f32 v29, v30, v31
	global_store_dwordx2 v[96:97], v[28:29], off
	s_nop 0
	v_pk_mul_f32 v[26:27], v[26:27], v[98:99] op_sel_hi:[1,0]
	v_pk_mul_f32 v[24:25], v[24:25], v[98:99] op_sel_hi:[1,0]
	v_pk_mul_f32 v[22:23], v[22:23], v[98:99] op_sel_hi:[1,0]
	v_pk_mul_f32 v[20:21], v[20:21], v[98:99] op_sel_hi:[1,0]
	v_pk_mul_f32 v[18:19], v[18:19], v[98:99] op_sel_hi:[1,0]
	v_pk_mul_f32 v[16:17], v[16:17], v[98:99] op_sel_hi:[1,0]
	v_pk_mul_f32 v[14:15], v[14:15], v[98:99] op_sel_hi:[1,0]
	v_pk_mul_f32 v[12:13], v[12:13], v[98:99] op_sel_hi:[1,0]
	v_pk_mul_f32 v[10:11], v[10:11], v[98:99] op_sel_hi:[1,0]
	v_pk_mul_f32 v[8:9], v[8:9], v[98:99] op_sel_hi:[1,0]
	v_pk_mul_f32 v[6:7], v[6:7], v[98:99] op_sel_hi:[1,0]
	v_pk_mul_f32 v[4:5], v[4:5], v[98:99] op_sel_hi:[1,0]
	v_pk_mul_f32 v[2:3], v[2:3], v[98:99] op_sel_hi:[1,0]
	v_pk_mul_f32 v[0:1], v[0:1], v[98:99] op_sel_hi:[1,0]
	s_waitcnt vmcnt(21)
	v_pk_mul_f32 v[24:25], v[100:101], v[24:25]
	v_pk_mul_f32 v[26:27], v[102:103], v[26:27]
	s_waitcnt vmcnt(20)
	v_pk_add_f32 v[28:29], v[106:107], 1.0 op_sel_hi:[1,0]
	v_pk_add_f32 v[30:31], v[104:105], 1.0 op_sel_hi:[1,0]
	s_waitcnt vmcnt(19)
	v_pk_fma_f32 v[26:27], v[28:29], v[26:27], v[110:111]
	v_pk_fma_f32 v[24:25], v[30:31], v[24:25], v[108:109]
	s_nop 0
	v_cvt_pk_bf16_f32 v24, v24, v25
	v_cvt_pk_bf16_f32 v25, v26, v27
	global_store_dwordx2 v[96:97], v[24:25], off offset:512
	s_nop 0
	s_waitcnt vmcnt(19)
	v_pk_mul_f32 v[20:21], v[112:113], v[20:21]
	v_pk_mul_f32 v[22:23], v[114:115], v[22:23]
	s_waitcnt vmcnt(18)
	v_pk_add_f32 v[24:25], v[118:119], 1.0 op_sel_hi:[1,0]
	v_pk_add_f32 v[26:27], v[116:117], 1.0 op_sel_hi:[1,0]
	s_waitcnt vmcnt(17)
	v_pk_fma_f32 v[22:23], v[24:25], v[22:23], v[122:123]
	v_pk_fma_f32 v[20:21], v[26:27], v[20:21], v[120:121]
	s_nop 0
	v_cvt_pk_bf16_f32 v20, v20, v21
	v_cvt_pk_bf16_f32 v21, v22, v23
	global_store_dwordx2 v[96:97], v[20:21], off offset:1024
	s_nop 0
	s_waitcnt vmcnt(17)
	v_pk_mul_f32 v[16:17], v[16:17], v[124:125]
	v_pk_mul_f32 v[18:19], v[18:19], v[126:127]
	s_waitcnt vmcnt(16)
	v_pk_add_f32 v[20:21], v[130:131], 1.0 op_sel_hi:[1,0]
	v_pk_add_f32 v[22:23], v[128:129], 1.0 op_sel_hi:[1,0]
	s_waitcnt vmcnt(15)
	v_pk_fma_f32 v[18:19], v[18:19], v[20:21], v[134:135]
	v_pk_fma_f32 v[16:17], v[16:17], v[22:23], v[132:133]
	s_nop 0
	v_cvt_pk_bf16_f32 v16, v16, v17
	v_cvt_pk_bf16_f32 v17, v18, v19
	global_store_dwordx2 v[96:97], v[16:17], off offset:1536
	s_nop 0
	s_waitcnt vmcnt(15)
	v_pk_mul_f32 v[12:13], v[12:13], v[136:137]
	v_pk_mul_f32 v[14:15], v[14:15], v[138:139]
	s_waitcnt vmcnt(14)
	v_pk_add_f32 v[16:17], v[142:143], 1.0 op_sel_hi:[1,0]
	v_pk_add_f32 v[18:19], v[140:141], 1.0 op_sel_hi:[1,0]
	s_waitcnt vmcnt(13)
	v_pk_fma_f32 v[14:15], v[14:15], v[16:17], v[190:191]
	v_pk_fma_f32 v[12:13], v[12:13], v[18:19], v[188:189]
	s_nop 0
	v_cvt_pk_bf16_f32 v12, v12, v13
	v_cvt_pk_bf16_f32 v13, v14, v15
	global_store_dwordx2 v[96:97], v[12:13], off offset:2048
	s_nop 0
	s_waitcnt vmcnt(13)
	v_pk_mul_f32 v[8:9], v[8:9], v[192:193]
	v_pk_mul_f32 v[10:11], v[10:11], v[194:195]
	s_waitcnt vmcnt(12)
	v_pk_add_f32 v[12:13], v[198:199], 1.0 op_sel_hi:[1,0]
	v_pk_add_f32 v[14:15], v[196:197], 1.0 op_sel_hi:[1,0]
	s_waitcnt vmcnt(11)
	v_pk_fma_f32 v[10:11], v[10:11], v[12:13], v[202:203]
	v_pk_fma_f32 v[8:9], v[8:9], v[14:15], v[200:201]
	s_nop 0
	v_cvt_pk_bf16_f32 v8, v8, v9
	v_cvt_pk_bf16_f32 v9, v10, v11
	global_store_dwordx2 v[96:97], v[8:9], off offset:2560
	s_nop 0
	s_waitcnt vmcnt(11)
	v_pk_mul_f32 v[4:5], v[4:5], v[204:205]
	v_pk_mul_f32 v[6:7], v[6:7], v[206:207]
	s_waitcnt vmcnt(10)
	v_pk_add_f32 v[8:9], v[210:211], 1.0 op_sel_hi:[1,0]
	v_pk_add_f32 v[10:11], v[208:209], 1.0 op_sel_hi:[1,0]
	s_waitcnt vmcnt(9)
	v_pk_fma_f32 v[6:7], v[6:7], v[8:9], v[214:215]
	v_pk_fma_f32 v[4:5], v[4:5], v[10:11], v[212:213]
	s_nop 0
	v_cvt_pk_bf16_f32 v4, v4, v5
	v_cvt_pk_bf16_f32 v5, v6, v7
	global_store_dwordx2 v[96:97], v[4:5], off offset:3072
	s_nop 0
	s_waitcnt vmcnt(9)
	v_pk_mul_f32 v[0:1], v[0:1], v[216:217]
	v_pk_mul_f32 v[2:3], v[2:3], v[218:219]
	s_waitcnt vmcnt(8)
	v_pk_add_f32 v[4:5], v[222:223], 1.0 op_sel_hi:[1,0]
	v_pk_add_f32 v[6:7], v[220:221], 1.0 op_sel_hi:[1,0]
	s_waitcnt vmcnt(7)
	v_pk_fma_f32 v[2:3], v[2:3], v[4:5], v[226:227]
	v_pk_fma_f32 v[0:1], v[0:1], v[6:7], v[224:225]
	s_nop 0
	v_cvt_pk_bf16_f32 v0, v0, v1
	v_cvt_pk_bf16_f32 v1, v2, v3
	global_store_dwordx2 v[96:97], v[0:1], off offset:3584
	s_cbranch_scc0 .LBB0_154

.LBB0_918:
	s_lshl_b64 s[0:1], s[20:21], 2
	s_add_u32 s12, s4, s0
	s_addc_u32 s13, s5, s1
	s_add_u32 s20, s12, 0x2000
	s_addc_u32 s21, s13, 0
	global_load_dwordx4 v[76:79], v[40:41], off
	global_load_dwordx4 v[80:83], v144, s[20:21]
	global_load_dwordx4 v[90:93], v144, s[12:13]
	global_load_dwordx4 v[100:103], v[40:41], off offset:1024
	global_load_dwordx4 v[104:107], v59, s[20:21]
	global_load_dwordx4 v[108:111], v144, s[12:13] offset:1024
	global_load_dwordx4 v[112:115], v[40:41], off offset:2048
	global_load_dwordx4 v[116:119], v63, s[20:21]
	global_load_dwordx4 v[120:123], v144, s[12:13] offset:2048
	global_load_dwordx4 v[124:127], v[40:41], off offset:3072
	global_load_dwordx4 v[128:131], v84, s[20:21]
	global_load_dwordx4 v[132:135], v144, s[12:13] offset:3072
	global_load_dwordx4 v[136:139], v[66:67], off
	global_load_dwordx4 v[140:143], v85, s[20:21]
	global_load_dwordx4 v[188:191], v85, s[12:13]
	global_load_dwordx4 v[192:195], v[68:69], off
	global_load_dwordx4 v[196:199], v86, s[20:21]
	global_load_dwordx4 v[200:203], v86, s[12:13]
	global_load_dwordx4 v[204:207], v[70:71], off
	global_load_dwordx4 v[208:211], v87, s[20:21]
	global_load_dwordx4 v[212:215], v87, s[12:13]
	global_load_dwordx4 v[216:219], v[72:73], off
	global_load_dwordx4 v[220:223], v88, s[20:21]
	global_load_dwordx4 v[224:227], v88, s[12:13]
	ds_bpermute_b32 v33, v37, v32
	s_mov_b32 s0, 0xe2000000
	s_add_i32 s14, s14, s34
	s_cmpk_lt_i32 s14, 0x3000
	s_waitcnt lgkmcnt(0)
	v_add_f32_e32 v32, v32, v33
	ds_bpermute_b32 v33, v45, v32
	s_waitcnt lgkmcnt(0)
	v_add_f32_e32 v32, v32, v33
	ds_bpermute_b32 v33, v47, v32
	s_waitcnt lgkmcnt(0)
	v_add_f32_e32 v32, v32, v33
	ds_bpermute_b32 v33, v49, v32
	s_waitcnt lgkmcnt(0)
	v_add_f32_e32 v32, v32, v33
	ds_bpermute_b32 v33, v51, v32
	s_waitcnt lgkmcnt(0)
	v_add_f32_e32 v32, v32, v33
	ds_bpermute_b32 v33, v55, v32
	s_waitcnt lgkmcnt(0)
	v_add_f32_e32 v32, v32, v33
	v_fmamk_f32 v32, v32, 0x3a000000, v181
	v_cmp_gt_f32_e32 vcc, s72, v32
	v_mul_f32_e32 v33, 0x4b800000, v32
	s_waitcnt vmcnt(22)
	v_pk_add_f32 v[34:35], v[82:83], 1.0 op_sel_hi:[1,0]
	v_cndmask_b32_e32 v32, v32, v33, vcc
	v_rsq_f32_e32 v32, v32
	s_nop 0
	v_mul_f32_e32 v33, 0x45800000, v32
	v_cndmask_b32_e32 v32, v32, v33, vcc
	v_pk_mul_f32 v[30:31], v[30:31], v[32:33] op_sel_hi:[1,0]
	v_pk_mul_f32 v[28:29], v[28:29], v[32:33] op_sel_hi:[1,0]
	v_pk_mul_f32 v[30:31], v[78:79], v[30:31]
	v_pk_mul_f32 v[28:29], v[76:77], v[28:29]
	v_pk_add_f32 v[76:77], v[80:81], 1.0 op_sel_hi:[1,0]
	s_waitcnt vmcnt(21)
	v_pk_fma_f32 v[30:31], v[34:35], v[30:31], v[92:93]
	v_pk_fma_f32 v[28:29], v[76:77], v[28:29], v[90:91]
	v_add_co_u32_e32 v34, vcc, s0, v74
	v_cvt_pk_bf16_f32 v28, v28, v29
	v_cvt_pk_bf16_f32 v29, v30, v31
	v_addc_co_u32_e32 v35, vcc, -1, v75, vcc
	global_store_dwordx2 v[34:35], v[28:29], off offset:-3584
	s_nop 0
	v_pk_mul_f32 v[26:27], v[26:27], v[32:33] op_sel_hi:[1,0]
	v_pk_mul_f32 v[24:25], v[24:25], v[32:33] op_sel_hi:[1,0]
	v_pk_mul_f32 v[22:23], v[22:23], v[32:33] op_sel_hi:[1,0]
	v_pk_mul_f32 v[20:21], v[20:21], v[32:33] op_sel_hi:[1,0]
	v_pk_mul_f32 v[18:19], v[18:19], v[32:33] op_sel_hi:[1,0]
	v_pk_mul_f32 v[16:17], v[16:17], v[32:33] op_sel_hi:[1,0]
	v_pk_mul_f32 v[14:15], v[14:15], v[32:33] op_sel_hi:[1,0]
	v_pk_mul_f32 v[12:13], v[12:13], v[32:33] op_sel_hi:[1,0]
	v_pk_mul_f32 v[10:11], v[10:11], v[32:33] op_sel_hi:[1,0]
	v_pk_mul_f32 v[8:9], v[8:9], v[32:33] op_sel_hi:[1,0]
	v_pk_mul_f32 v[6:7], v[6:7], v[32:33] op_sel_hi:[1,0]
	v_pk_mul_f32 v[4:5], v[4:5], v[32:33] op_sel_hi:[1,0]
	v_pk_mul_f32 v[2:3], v[2:3], v[32:33] op_sel_hi:[1,0]
	v_pk_mul_f32 v[0:1], v[0:1], v[32:33] op_sel_hi:[1,0]
	v_lshl_add_u64 v[74:75], v[74:75], 0, s[42:43]
	s_waitcnt vmcnt(21)
	v_pk_mul_f32 v[24:25], v[100:101], v[24:25]
	v_pk_mul_f32 v[26:27], v[102:103], v[26:27]
	s_waitcnt vmcnt(20)
	v_pk_add_f32 v[28:29], v[106:107], 1.0 op_sel_hi:[1,0]
	v_pk_add_f32 v[30:31], v[104:105], 1.0 op_sel_hi:[1,0]
	s_waitcnt vmcnt(19)
	v_pk_fma_f32 v[26:27], v[28:29], v[26:27], v[110:111]
	v_pk_fma_f32 v[24:25], v[30:31], v[24:25], v[108:109]
	s_nop 0
	v_cvt_pk_bf16_f32 v24, v24, v25
	v_cvt_pk_bf16_f32 v25, v26, v27
	global_store_dwordx2 v[34:35], v[24:25], off offset:-3072
	s_nop 0
	s_waitcnt vmcnt(19)
	v_pk_mul_f32 v[20:21], v[112:113], v[20:21]
	v_pk_mul_f32 v[22:23], v[114:115], v[22:23]
	s_waitcnt vmcnt(18)
	v_pk_add_f32 v[24:25], v[118:119], 1.0 op_sel_hi:[1,0]
	v_pk_add_f32 v[26:27], v[116:117], 1.0 op_sel_hi:[1,0]
	s_waitcnt vmcnt(17)
	v_pk_fma_f32 v[22:23], v[24:25], v[22:23], v[122:123]
	v_pk_fma_f32 v[20:21], v[26:27], v[20:21], v[120:121]
	s_nop 0
	v_cvt_pk_bf16_f32 v20, v20, v21
	v_cvt_pk_bf16_f32 v21, v22, v23
	global_store_dwordx2 v[34:35], v[20:21], off offset:-2560
	s_nop 0
	s_waitcnt vmcnt(17)
	v_pk_mul_f32 v[16:17], v[16:17], v[124:125]
	v_pk_mul_f32 v[18:19], v[18:19], v[126:127]
	s_waitcnt vmcnt(16)
	v_pk_add_f32 v[20:21], v[130:131], 1.0 op_sel_hi:[1,0]
	v_pk_add_f32 v[22:23], v[128:129], 1.0 op_sel_hi:[1,0]
	s_waitcnt vmcnt(15)
	v_pk_fma_f32 v[18:19], v[18:19], v[20:21], v[134:135]
	v_pk_fma_f32 v[16:17], v[16:17], v[22:23], v[132:133]
	s_nop 0
	v_cvt_pk_bf16_f32 v16, v16, v17
	v_cvt_pk_bf16_f32 v17, v18, v19
	global_store_dwordx2 v[34:35], v[16:17], off offset:-2048
	s_nop 0
	s_waitcnt vmcnt(15)
	v_pk_mul_f32 v[12:13], v[12:13], v[136:137]
	v_pk_mul_f32 v[14:15], v[14:15], v[138:139]
	s_waitcnt vmcnt(14)
	v_pk_add_f32 v[16:17], v[142:143], 1.0 op_sel_hi:[1,0]
	v_pk_add_f32 v[18:19], v[140:141], 1.0 op_sel_hi:[1,0]
	s_waitcnt vmcnt(13)
	v_pk_fma_f32 v[14:15], v[14:15], v[16:17], v[190:191]
	v_pk_fma_f32 v[12:13], v[12:13], v[18:19], v[188:189]
	s_nop 0
	v_cvt_pk_bf16_f32 v12, v12, v13
	v_cvt_pk_bf16_f32 v13, v14, v15
	global_store_dwordx2 v[34:35], v[12:13], off offset:-1536
	s_nop 0
	s_waitcnt vmcnt(13)
	v_pk_mul_f32 v[8:9], v[8:9], v[192:193]
	v_pk_mul_f32 v[10:11], v[10:11], v[194:195]
	s_waitcnt vmcnt(12)
	v_pk_add_f32 v[12:13], v[198:199], 1.0 op_sel_hi:[1,0]
	v_pk_add_f32 v[14:15], v[196:197], 1.0 op_sel_hi:[1,0]
	s_waitcnt vmcnt(11)
	v_pk_fma_f32 v[10:11], v[10:11], v[12:13], v[202:203]
	v_pk_fma_f32 v[8:9], v[8:9], v[14:15], v[200:201]
	s_nop 0
	v_cvt_pk_bf16_f32 v8, v8, v9
	v_cvt_pk_bf16_f32 v9, v10, v11
	global_store_dwordx2 v[34:35], v[8:9], off offset:-1024
	s_nop 0
	s_waitcnt vmcnt(11)
	v_pk_mul_f32 v[4:5], v[4:5], v[204:205]
	v_pk_mul_f32 v[6:7], v[6:7], v[206:207]
	s_waitcnt vmcnt(10)
	v_pk_add_f32 v[8:9], v[210:211], 1.0 op_sel_hi:[1,0]
	v_pk_add_f32 v[10:11], v[208:209], 1.0 op_sel_hi:[1,0]
	s_waitcnt vmcnt(9)
	v_pk_fma_f32 v[6:7], v[6:7], v[8:9], v[214:215]
	v_pk_fma_f32 v[4:5], v[4:5], v[10:11], v[212:213]
	s_nop 0
	v_cvt_pk_bf16_f32 v4, v4, v5
	v_cvt_pk_bf16_f32 v5, v6, v7
	global_store_dwordx2 v[34:35], v[4:5], off offset:-512
	s_nop 0
	s_waitcnt vmcnt(9)
	v_pk_mul_f32 v[0:1], v[0:1], v[216:217]
	v_pk_mul_f32 v[2:3], v[2:3], v[218:219]
	s_waitcnt vmcnt(8)
	v_pk_add_f32 v[4:5], v[222:223], 1.0 op_sel_hi:[1,0]
	v_pk_add_f32 v[6:7], v[220:221], 1.0 op_sel_hi:[1,0]
	s_waitcnt vmcnt(7)
	v_pk_fma_f32 v[2:3], v[2:3], v[4:5], v[226:227]
	v_pk_fma_f32 v[0:1], v[0:1], v[6:7], v[224:225]
	s_nop 0
	v_cvt_pk_bf16_f32 v0, v0, v1
	v_cvt_pk_bf16_f32 v1, v2, v3
	global_store_dwordx2 v[34:35], v[0:1], off
	s_cbranch_scc0 .LBB0_930

.LBB0_926:
	s_cmpk_gt_i32 s14, 0x1fff
	s_cselect_b64 s[0:1], -1, 0
	s_and_b64 s[0:1], s[16:17], s[0:1]
	v_cndmask_b32_e64 v32, 0, 1, s[0:1]
	v_cmp_ne_u32_e64 s[12:13], 1, v32
	s_andn2_b64 vcc, exec, s[0:1]
	s_cbranch_vccnz .LBB0_928
	s_add_i32 s58, s14, 0xffffe000
	s_lshl_b64 s[0:1], s[58:59], 12
	s_add_u32 s24, s8, s0
	s_addc_u32 s25, s9, s1
	s_add_u32 s22, s24, 0x1000000
	v_lshlrev_b32_e32 v34, 3, v36
	s_addc_u32 s23, s25, 0
	global_load_dwordx2 v[32:33], v34, s[24:25]
	global_load_dwordx2 v[80:81], v34, s[22:23]
	global_load_dwordx4 v[76:79], v[42:43], off
	global_load_dwordx2 v[100:101], v34, s[24:25] offset:512
	v_lshlrev_b32_e32 v102, 3, v44
	global_load_dwordx2 v[104:105], v102, s[22:23]
	global_load_dwordx4 v[106:109], v[42:43], off offset:1024
	global_load_dwordx2 v[110:111], v34, s[24:25] offset:1024
	v_lshlrev_b32_e32 v112, 3, v46
	global_load_dwordx2 v[114:115], v112, s[22:23]
	global_load_dwordx4 v[116:119], v[42:43], off offset:2048
	global_load_dwordx2 v[120:121], v34, s[24:25] offset:1536
	v_lshlrev_b32_e32 v122, 3, v48
	global_load_dwordx2 v[124:125], v122, s[22:23]
	global_load_dwordx4 v[126:129], v[42:43], off offset:3072
	global_load_dwordx2 v[130:131], v34, s[24:25] offset:2048
	v_lshlrev_b32_e32 v132, 3, v50
	global_load_dwordx2 v[134:135], v132, s[22:23]
	global_load_dwordx4 v[136:139], v[52:53], off
	global_load_dwordx2 v[140:141], v34, s[24:25] offset:2560
	v_lshlrev_b32_e32 v142, 3, v54
	global_load_dwordx2 v[188:189], v142, s[22:23]
	global_load_dwordx4 v[190:193], v[56:57], off
	global_load_dwordx2 v[194:195], v34, s[24:25] offset:3072
	v_lshlrev_b32_e32 v196, 3, v58
	global_load_dwordx2 v[198:199], v196, s[22:23]
	global_load_dwordx4 v[200:203], v[60:61], off
	global_load_dwordx2 v[204:205], v34, s[24:25] offset:3584
	v_lshlrev_b32_e32 v206, 3, v62
	global_load_dwordx2 v[208:209], v206, s[22:23]
	global_load_dwordx4 v[210:213], v[64:65], off
	v_lshlrev_b32_e32 v35, 3, v44
	s_waitcnt vmcnt(23)
	v_lshlrev_b32_e32 v82, 16, v32
	v_and_b32_e32 v83, 0xffff0000, v32
	v_lshlrev_b32_e32 v32, 16, v33
	v_and_b32_e32 v33, 0xffff0000, v33
	s_waitcnt vmcnt(22)
	v_lshlrev_b32_e32 v90, 16, v80
	v_and_b32_e32 v91, 0xffff0000, v80
	v_lshlrev_b32_e32 v80, 16, v81
	v_and_b32_e32 v81, 0xffff0000, v81
	v_pk_add_f32 v[32:33], v[32:33], v[80:81]
	v_pk_add_f32 v[82:83], v[82:83], v[90:91]
	s_waitcnt vmcnt(21)
	v_pk_fma_f32 v[30:31], v[78:79], v[32:33], v[30:31]
	v_pk_fma_f32 v[28:29], v[76:77], v[82:83], v[28:29]
	v_lshlrev_b32_e32 v35, 3, v46
	s_waitcnt vmcnt(20)
	v_lshlrev_b32_e32 v82, 16, v100
	v_and_b32_e32 v83, 0xffff0000, v100
	s_waitcnt vmcnt(19)
	v_lshlrev_b32_e32 v90, 16, v104
	v_and_b32_e32 v91, 0xffff0000, v104
	v_lshlrev_b32_e32 v32, 16, v101
	v_and_b32_e32 v33, 0xffff0000, v101
	v_lshlrev_b32_e32 v80, 16, v105
	v_and_b32_e32 v81, 0xffff0000, v105
	v_pk_add_f32 v[82:83], v[82:83], v[90:91]
	v_pk_add_f32 v[32:33], v[32:33], v[80:81]
	s_waitcnt vmcnt(18)
	v_pk_fma_f32 v[24:25], v[106:107], v[82:83], v[24:25]
	v_pk_fma_f32 v[26:27], v[108:109], v[32:33], v[26:27]
	v_mov_b32_e32 v76, v29
	v_mov_b32_e32 v77, v25
	v_mov_b32_e32 v32, v28
	v_mov_b32_e32 v33, v24
	v_pk_mul_f32 v[76:77], v[76:77], v[76:77]
	v_mov_b32_e32 v78, v31
	v_mov_b32_e32 v79, v27
	v_pk_fma_f32 v[32:33], v[32:33], v[32:33], v[76:77]
	v_mov_b32_e32 v76, v30
	v_mov_b32_e32 v77, v26
	v_pk_mul_f32 v[78:79], v[78:79], v[78:79]
	v_pk_fma_f32 v[76:77], v[76:77], v[76:77], v[78:79]
	s_waitcnt vmcnt(17)
	v_lshlrev_b32_e32 v90, 16, v110
	v_pk_add_f32 v[32:33], v[32:33], v[76:77]
	v_and_b32_e32 v91, 0xffff0000, v110
	v_lshlrev_b32_e32 v80, 16, v111
	v_and_b32_e32 v81, 0xffff0000, v111
	v_lshlrev_b32_e32 v35, 3, v48
	v_pk_add_f32 v[32:33], v[32:33], v[32:33] op_sel:[0,1] op_sel_hi:[1,0]
	s_waitcnt vmcnt(16)
	v_lshlrev_b32_e32 v92, 16, v114
	v_and_b32_e32 v93, 0xffff0000, v114
	v_lshlrev_b32_e32 v82, 16, v115
	v_and_b32_e32 v83, 0xffff0000, v115
	v_pk_add_f32 v[80:81], v[80:81], v[82:83]
	v_pk_add_f32 v[82:83], v[90:91], v[92:93]
	s_waitcnt vmcnt(15)
	v_pk_fma_f32 v[22:23], v[118:119], v[80:81], v[22:23]
	v_pk_fma_f32 v[20:21], v[116:117], v[82:83], v[20:21]
	v_pk_mul_f32 v[76:77], v[22:23], v[22:23]
	v_pk_mul_f32 v[78:79], v[20:21], v[20:21]
	v_pk_mov_b32 v[80:81], v[78:79], v[76:77] op_sel:[1,0]
	v_mov_b32_e32 v79, v77
	v_pk_add_f32 v[80:81], v[80:81], v[78:79]
	v_lshlrev_b32_e32 v35, 3, v50
	s_waitcnt vmcnt(14)
	v_lshlrev_b32_e32 v92, 16, v120
	v_and_b32_e32 v93, 0xffff0000, v120
	v_lshlrev_b32_e32 v82, 16, v121
	v_and_b32_e32 v83, 0xffff0000, v121
	s_waitcnt vmcnt(13)
	v_lshlrev_b32_e32 v94, 16, v124
	v_and_b32_e32 v95, 0xffff0000, v124
	v_lshlrev_b32_e32 v90, 16, v125
	v_and_b32_e32 v91, 0xffff0000, v125
	v_pk_add_f32 v[82:83], v[82:83], v[90:91]
	v_pk_add_f32 v[92:93], v[92:93], v[94:95]
	s_waitcnt vmcnt(12)
	v_pk_fma_f32 v[18:19], v[128:129], v[82:83], v[18:19]
	v_pk_fma_f32 v[16:17], v[126:127], v[92:93], v[16:17]
	s_waitcnt vmcnt(11)
	v_lshlrev_b32_e32 v92, 16, v130
	v_and_b32_e32 v93, 0xffff0000, v130
	s_waitcnt vmcnt(10)
	v_lshlrev_b32_e32 v94, 16, v134
	v_and_b32_e32 v95, 0xffff0000, v134
	v_lshlrev_b32_e32 v82, 16, v131
	v_and_b32_e32 v83, 0xffff0000, v131
	v_lshlrev_b32_e32 v90, 16, v135
	v_and_b32_e32 v91, 0xffff0000, v135
	v_pk_add_f32 v[92:93], v[92:93], v[94:95]
	v_pk_add_f32 v[82:83], v[82:83], v[90:91]
	s_waitcnt vmcnt(9)
	v_pk_fma_f32 v[12:13], v[136:137], v[92:93], v[12:13]
	v_pk_fma_f32 v[14:15], v[138:139], v[82:83], v[14:15]
	v_mul_f32_e32 v35, v12, v12
	v_mul_f32_e32 v78, v13, v13
	v_pk_add_f32 v[76:77], v[80:81], v[80:81] op_sel:[0,1] op_sel_hi:[1,0]
	v_mov_b32_e32 v33, v35
	v_mov_b32_e32 v77, v78
	v_pk_add_f32 v[32:33], v[32:33], v[76:77]
	v_mul_f32_e32 v76, v17, v17
	v_mul_f32_e32 v79, v14, v14
	v_pk_fma_f32 v[76:77], v[16:17], v[16:17], v[76:77] op_sel_hi:[1,1,0]
	v_mul_f32_e32 v78, v19, v19
	v_mul_f32_e32 v82, v15, v15
	v_mov_b32_e32 v77, v79
	v_pk_fma_f32 v[78:79], v[18:19], v[18:19], v[78:79] op_sel_hi:[1,1,0]
	v_lshlrev_b32_e32 v35, 3, v54
	v_mov_b32_e32 v79, v82
	v_pk_add_f32 v[76:77], v[76:77], v[78:79]
	s_nop 0
	v_pk_add_f32 v[76:77], v[32:33], v[76:77]
	v_lshlrev_b32_e32 v35, 3, v58
	s_waitcnt vmcnt(8)
	v_lshlrev_b32_e32 v90, 16, v140
	v_and_b32_e32 v91, 0xffff0000, v140
	v_lshlrev_b32_e32 v32, 16, v141
	v_and_b32_e32 v33, 0xffff0000, v141
	s_waitcnt vmcnt(7)
	v_lshlrev_b32_e32 v92, 16, v188
	v_and_b32_e32 v93, 0xffff0000, v188
	v_lshlrev_b32_e32 v82, 16, v189
	v_and_b32_e32 v83, 0xffff0000, v189
	v_pk_add_f32 v[32:33], v[32:33], v[82:83]
	v_pk_add_f32 v[82:83], v[90:91], v[92:93]
	s_waitcnt vmcnt(6)
	v_pk_fma_f32 v[10:11], v[192:193], v[32:33], v[10:11]
	v_pk_fma_f32 v[8:9], v[190:191], v[82:83], v[8:9]
	v_pk_mul_f32 v[32:33], v[10:11], v[10:11]
	v_pk_mul_f32 v[78:79], v[8:9], v[8:9]
	s_nop 0
	v_pk_mov_b32 v[80:81], v[78:79], v[32:33] op_sel:[1,0]
	v_mov_b32_e32 v79, v33
	v_pk_add_f32 v[78:79], v[80:81], v[78:79]
	s_waitcnt vmcnt(5)
	v_lshlrev_b32_e32 v92, 16, v194
	v_and_b32_e32 v93, 0xffff0000, v194
	v_lshlrev_b32_e32 v32, 16, v195
	v_and_b32_e32 v33, 0xffff0000, v195
	s_waitcnt vmcnt(4)
	v_lshlrev_b32_e32 v94, 16, v198
	v_and_b32_e32 v95, 0xffff0000, v198
	v_lshlrev_b32_e32 v90, 16, v199
	v_and_b32_e32 v91, 0xffff0000, v199
	v_pk_add_f32 v[32:33], v[32:33], v[90:91]
	v_pk_add_f32 v[90:91], v[92:93], v[94:95]
	s_waitcnt vmcnt(3)
	v_pk_fma_f32 v[6:7], v[202:203], v[32:33], v[6:7]
	v_pk_fma_f32 v[4:5], v[200:201], v[90:91], v[4:5]
	v_lshlrev_b32_e32 v32, 3, v62
	s_nop 0
	s_waitcnt vmcnt(2)
	v_lshlrev_b32_e32 v90, 16, v204
	v_and_b32_e32 v91, 0xffff0000, v204
	s_waitcnt vmcnt(1)
	v_lshlrev_b32_e32 v92, 16, v208
	v_and_b32_e32 v93, 0xffff0000, v208
	v_lshlrev_b32_e32 v80, 16, v205
	v_and_b32_e32 v81, 0xffff0000, v205
	v_lshlrev_b32_e32 v82, 16, v209
	v_and_b32_e32 v83, 0xffff0000, v209
	v_pk_add_f32 v[90:91], v[90:91], v[92:93]
	v_pk_add_f32 v[80:81], v[80:81], v[82:83]
	s_waitcnt vmcnt(0)
	v_pk_fma_f32 v[0:1], v[210:211], v[90:91], v[0:1]
	v_pk_fma_f32 v[2:3], v[212:213], v[80:81], v[2:3]
	v_mul_f32_e32 v34, v0, v0
	v_pk_add_f32 v[32:33], v[76:77], v[76:77] op_sel:[0,1] op_sel_hi:[1,0]
	v_mul_f32_e32 v80, v1, v1
	v_mov_b32_e32 v33, v34
	v_pk_add_f32 v[34:35], v[78:79], v[78:79] op_sel:[0,1] op_sel_hi:[1,0]
	v_mul_f32_e32 v76, v7, v7
	v_mov_b32_e32 v35, v80
	v_pk_add_f32 v[32:33], v[32:33], v[34:35]
	v_mul_f32_e32 v34, v5, v5
	v_mul_f32_e32 v81, v2, v2
	v_mul_f32_e32 v82, v3, v3
	v_pk_fma_f32 v[34:35], v[4:5], v[4:5], v[34:35] op_sel_hi:[1,1,0]
	v_pk_fma_f32 v[76:77], v[6:7], v[6:7], v[76:77] op_sel_hi:[1,1,0]
	v_mov_b32_e32 v35, v81
	v_mov_b32_e32 v77, v82
	v_pk_add_f32 v[34:35], v[34:35], v[76:77]
	s_nop 0
	v_pk_add_f32 v[32:33], v[32:33], v[34:35]
	s_nop 0
	v_add_f32_e32 v32, v32, v33
	s_and_b64 vcc, exec, s[12:13]
	s_cbranch_vccnz .LBB0_918
	s_branch .LBB0_917
